# P4: first row's norm partial loads issued at the start of the last K iteration, epilogue top waits only for them, second row summed before the fifth row group
# baseline (speedup 1.0000x reference)
.LBB0_328:
	s_cmp_lg_u32 s17, 12
	s_cbranch_scc1 .Lp4_noearly
	v_mov_b32_e32 v252, s8
	v_lshl_add_u32 v252, v252, 8, v1
	v_bfe_u32 v253, v0, 4, 2
	v_lshl_add_u32 v252, v253, 4, v252
	v_mov_b32_e32 v253, 0
	v_lshlrev_b64 v[252:253], 6, v[252:253]
	v_lshl_add_u64 v[252:253], s[30:31], 0, v[252:253]
	global_load_dwordx4 v[236:239], v[252:253], off
	global_load_dwordx4 v[240:243], v[252:253], off offset:16
	global_load_dwordx4 v[244:247], v[252:253], off offset:32
	global_load_dwordx4 v[248:251], v[252:253], off offset:48

.LBB0_331:
	v_lshl_add_u32 v154, s8, 8, v1
	v_ashrrev_i32_e32 v155, 31, v154
	v_lshlrev_b64 v[156:157], 6, v[154:155]
	v_lshl_add_u64 v[156:157], s[30:31], 0, v[156:157]
	v_mov_b32_e32 v226, 0x2000
	v_mov_b32_e32 v227, 0
	v_lshl_add_u64 v[252:253], v[252:253], 0, v[226:227]
	global_load_dwordx4 v[210:213], v[252:253], off
	global_load_dwordx4 v[214:217], v[252:253], off offset:16
	global_load_dwordx4 v[218:221], v[252:253], off offset:32
	global_load_dwordx4 v[222:225], v[252:253], off offset:48
	s_waitcnt vmcnt(12)
	v_pk_add_f32 v[226:227], v[238:239], v[242:243]
	v_pk_add_f32 v[228:229], v[236:237], v[240:241]
	v_pk_add_f32 v[230:231], v[246:247], v[250:251]
	v_pk_add_f32 v[232:233], v[244:245], v[248:249]
	v_pk_add_f32 v[226:227], v[226:227], v[230:231]
	v_pk_add_f32 v[228:229], v[228:229], v[232:233]
	s_nop 0
	v_pk_mov_b32 v[230:231], v[228:229], v[226:227] op_sel:[1,0]
	v_mov_b32_e32 v229, v227
	v_pk_add_f32 v[228:229], v[230:231], v[228:229]
	s_nop 0
	v_add_f32_e32 v234, v228, v229
	v_mov_b32_e32 v235, v234
	s_nop 1
	v_permlane16_swap_b32_e32 v234, v235
	v_mov_b32_e32 v236, v234
	v_mov_b32_e32 v237, v235
	s_nop 1
	v_permlane32_swap_b32_e32 v234, v236
	v_permlane32_swap_b32_e32 v235, v237
	v_and_b32_e32 v250, 16, v0
	v_lshrrev_b32_e32 v251, 1, v250
	v_add_u32_e32 v250, v250, v251
	v_mov_b32_e32 v251, 0
	s_cmp_gt_i32 s18, 3
	s_cselect_b64 s[20:21], -1, 0
	s_cmp_lg_u32 s18, 4
	s_cselect_b64 s[22:23], -1, 0
	s_cmp_lt_i32 s18, 2
	s_cselect_b64 s[84:85], -1, 0
	s_cmp_gt_i32 s18, 1
	s_mov_b64 s[8:9], -1
	s_cselect_b64 s[38:39], -1, 0
	s_and_b64 vcc, exec, s[20:21]
	s_nop 0
	s_nop 0
	v_mov_b32_e32 v134, v234
	v_fmamk_f32 v134, v134, 0x3a800000, v162
	v_rsq_f32_e32 v134, v134
	s_nop 0
	v_pk_mul_f32 v[128:129], v[128:129], v[134:135] op_sel_hi:[1,0]
	v_pk_mul_f32 v[126:127], v[126:127], v[134:135] op_sel_hi:[1,0]
	v_pk_mul_f32 v[124:125], v[124:125], v[134:135] op_sel_hi:[1,0]
	v_pk_mul_f32 v[122:123], v[122:123], v[134:135] op_sel_hi:[1,0]
	v_pk_mul_f32 v[120:121], v[120:121], v[134:135] op_sel_hi:[1,0]
	v_pk_mul_f32 v[118:119], v[118:119], v[134:135] op_sel_hi:[1,0]
	v_pk_mul_f32 v[116:117], v[116:117], v[134:135] op_sel_hi:[1,0]
	v_pk_mul_f32 v[114:115], v[114:115], v[134:135] op_sel_hi:[1,0]
	s_cbranch_vccz .LBB0_343
	v_mul_f32_e32 v134, v127, v127
	v_mul_f32_e32 v156, v129, v129
	v_fmac_f32_e32 v134, v126, v126
	v_fmac_f32_e32 v156, v128, v128
	v_add_f32_e32 v166, v134, v156
	s_and_b64 vcc, exec, s[22:23]
	v_lshlrev_b64 v[156:157], 9, v[154:155]
	v_mul_f32_e32 v167, v123, v123
	v_mul_f32_e32 v168, v125, v125
	s_cbranch_vccz .LBB0_338
	v_fma_f32 v134, v122, v122, v167
	v_fma_f32 v169, v124, v124, v168
	v_and_b32_e32 v173, 64, v163
	v_add_f32_e32 v134, v134, v169
	v_xor_b32_e32 v169, 16, v163
	v_add_u32_e32 v176, 64, v173
	v_cmp_lt_i32_e32 vcc, v169, v176
	v_add_f32_e32 v134, v166, v134
	v_lshlrev_b64 v[174:175], 8, v[154:155]
	v_cndmask_b32_e32 v169, v163, v169, vcc
	v_lshlrev_b32_e32 v169, 2, v169
	ds_bpermute_b32 v169, v169, v134
	v_lshl_add_u64 v[170:171], v[140:141], 0, v[156:157]
	v_lshl_add_u64 v[174:175], v[142:143], 0, v[174:175]
	global_store_dwordx4 v[170:171], v[126:129], off
	v_cvt_pk_bf16_f32 v172, v126, v127
	s_waitcnt lgkmcnt(0)
	v_add_f32_e32 v134, v134, v169
	v_xor_b32_e32 v169, 32, v163
	v_cmp_lt_i32_e32 vcc, v169, v176
	v_cvt_pk_bf16_f32 v173, v128, v129
	global_store_dwordx2 v[174:175], v[172:173], off
	global_store_dwordx4 v[170:171], v[122:125], off offset:64
	v_cndmask_b32_e32 v169, v163, v169, vcc
	v_lshlrev_b32_e32 v169, 2, v169
	ds_bpermute_b32 v169, v169, v134
	v_cvt_pk_bf16_f32 v170, v122, v123
	v_cvt_pk_bf16_f32 v171, v124, v125
	global_store_dwordx2 v[174:175], v[170:171], off offset:32
	s_and_saveexec_b64 s[8:9], s[4:5]
	s_cbranch_execz .LBB0_335
	v_lshlrev_b64 v[170:171], 5, v[154:155]
	v_lshl_add_u64 v[170:171], s[42:43], 0, v[170:171]
	s_waitcnt lgkmcnt(0)
	v_add_f32_e32 v134, v134, v169
	global_store_dword v[170:171], v134, off offset:16

.LBB0_419:
	v_add_u32_e32 v66, 0x80, v154
	v_ashrrev_i32_e32 v67, 31, v66
	v_lshlrev_b64 v[68:69], 6, v[66:67]
	v_lshl_add_u64 v[80:81], s[30:31], 0, v[68:69]
	s_nop 0
	s_and_b64 vcc, exec, s[12:13]
	s_mov_b64 s[14:15], -1
	s_nop 0
	s_nop 0
	s_waitcnt vmcnt(8)
	v_pk_add_f32 v[226:227], v[212:213], v[216:217]
	v_pk_add_f32 v[228:229], v[210:211], v[214:215]
	v_pk_add_f32 v[230:231], v[220:221], v[224:225]
	v_pk_add_f32 v[232:233], v[218:219], v[222:223]
	v_pk_add_f32 v[226:227], v[226:227], v[230:231]
	v_pk_add_f32 v[228:229], v[228:229], v[232:233]
	s_nop 0
	v_pk_mov_b32 v[230:231], v[228:229], v[226:227] op_sel:[1,0]
	v_mov_b32_e32 v229, v227
	v_pk_add_f32 v[228:229], v[230:231], v[228:229]
	s_nop 0
	v_add_f32_e32 v238, v228, v229
	v_mov_b32_e32 v239, v238
	s_nop 1
	v_permlane16_swap_b32_e32 v238, v239
	v_mov_b32_e32 v240, v238
	v_mov_b32_e32 v241, v239
	s_nop 1
	v_permlane32_swap_b32_e32 v238, v240
	v_permlane32_swap_b32_e32 v239, v241
	v_mov_b32_e32 v68, v238
	v_fmamk_f32 v68, v68, 0x3a800000, v162
	v_rsq_f32_e32 v68, v68
	s_nop 0
	v_pk_mul_f32 v[64:65], v[64:65], v[68:69] op_sel_hi:[1,0]
	v_pk_mul_f32 v[62:63], v[62:63], v[68:69] op_sel_hi:[1,0]
	v_pk_mul_f32 v[60:61], v[60:61], v[68:69] op_sel_hi:[1,0]
	v_pk_mul_f32 v[58:59], v[58:59], v[68:69] op_sel_hi:[1,0]
	v_pk_mul_f32 v[56:57], v[56:57], v[68:69] op_sel_hi:[1,0]
	v_pk_mul_f32 v[54:55], v[54:55], v[68:69] op_sel_hi:[1,0]
	v_pk_mul_f32 v[52:53], v[52:53], v[68:69] op_sel_hi:[1,0]
	v_pk_mul_f32 v[50:51], v[50:51], v[68:69] op_sel_hi:[1,0]
	s_cbranch_vccnz .LBB0_431
	v_mul_f32_e32 v68, v63, v63
	v_mul_f32_e32 v69, v65, v65
	v_fmac_f32_e32 v68, v62, v62
	v_fmac_f32_e32 v69, v64, v64
	v_add_f32_e32 v70, v68, v69
	s_and_b64 vcc, exec, s[10:11]
	v_lshlrev_b64 v[68:69], 9, v[66:67]
	v_mul_f32_e32 v71, v59, v59
	v_mul_f32_e32 v72, v61, v61
	s_cbranch_vccnz .LBB0_426
	v_fma_f32 v73, v58, v58, v71
	v_fma_f32 v75, v60, v60, v72
	v_and_b32_e32 v78, 64, v163
	v_add_f32_e32 v73, v73, v75
	v_xor_b32_e32 v75, 16, v163
	v_add_u32_e32 v80, 64, v78
	v_cmp_lt_i32_e32 vcc, v75, v80
	v_add_f32_e32 v73, v70, v73
	v_lshl_add_u64 v[76:77], v[140:141], 0, v[68:69]
	v_cndmask_b32_e32 v75, v163, v75, vcc
	v_lshlrev_b32_e32 v75, 2, v75
	ds_bpermute_b32 v81, v75, v73
	v_lshlrev_b64 v[78:79], 8, v[66:67]
	global_store_dwordx4 v[76:77], v[62:65], off
	v_cvt_pk_bf16_f32 v74, v62, v63
	v_lshl_add_u64 v[78:79], v[142:143], 0, v[78:79]
	v_cvt_pk_bf16_f32 v75, v64, v65
	global_store_dwordx2 v[78:79], v[74:75], off
	v_xor_b32_e32 v74, 32, v163
	v_cmp_lt_i32_e32 vcc, v74, v80
	s_waitcnt lgkmcnt(0)
	v_add_f32_e32 v73, v73, v81
	global_store_dwordx4 v[76:77], v[58:61], off offset:64
	v_cndmask_b32_e32 v74, v163, v74, vcc
	v_lshlrev_b32_e32 v74, 2, v74
	ds_bpermute_b32 v74, v74, v73
	v_cvt_pk_bf16_f32 v76, v58, v59
	v_cvt_pk_bf16_f32 v77, v60, v61
	global_store_dwordx2 v[78:79], v[76:77], off offset:32
	s_and_saveexec_b64 s[14:15], s[4:5]
	s_cbranch_execz .LBB0_423
	v_lshlrev_b64 v[76:77], 5, v[66:67]
	v_lshl_add_u64 v[76:77], s[42:43], 0, v[76:77]
	s_waitcnt lgkmcnt(0)
	v_add_f32_e32 v73, v73, v74
	global_store_dword v[76:77], v73, off offset:16
